# dropped the workgroup barrier between the last W_in unit and the weight-copy tail (the seam barrier follows; the tail uses no LDS) so early waves start converting at once
# speedup vs baseline: 1.0044x; 1.0017x over previous
; #define PG8_WAIT_V(n) asm volatile("s_waitcnt vmcnt(" #n ")" ::: "memory")
; #define PG8_BAR __builtin_amdgcn_s_barrier()
;     ...
;     PG8_WAIT_V(0);
;     if constexpr (!ALIGN_EPI) { if (wr == 0) PG8_BAR; }
;     PG8_BAR;
; __global__ void __launch_bounds__(NWAVES * 64, 2) fwd_kernel(Args args) {
;     ...
;         if (G == 256 && bx >= 128) {
;             int tl_ = threadIdx.x; asm volatile("" : "+v"(tl_));
;             convert_weights(args, WI_P1 + WI_OUT, WI_ALL, (bx - 128) * NWAVES + wave, 128 * NWAVES, tl_ & 63);
;         }
.LBB0_404:
	v_readlane_b32 s76, v254, 38
	v_readlane_b32 s79, v254, 41
	s_mov_b64 s[72:73], s[84:85]
	s_mov_b32 s79, s88
	s_mov_b32 s84, s89
	v_readlane_b32 s92, v254, 36
	v_readlane_b32 s94, v254, 34
	v_readlane_b32 s96, v254, 32
	v_readlane_b32 s70, v254, 27
	v_readlane_b32 s88, v254, 30
	v_readlane_b32 s77, v254, 39
	v_readlane_b32 s78, v254, 40
	v_readlane_b32 s93, v254, 37
	v_readlane_b32 s95, v254, 35
	v_readlane_b32 s97, v254, 33
	v_readlane_b32 s71, v254, 28
	v_readlane_b32 s89, v254, 31
	v_readlane_b32 s85, v254, 29
.LBB0_405:
	s_cmpk_lt_i32 s10, 0x80
	s_cselect_b64 s[0:1], -1, 0
	s_xor_b64 s[2:3], s[88:89], -1
	s_or_b64 s[0:1], s[0:1], s[2:3]
	s_and_b64 vcc, exec, s[0:1]
	s_cbranch_vccnz .LBB0_453
	s_lshl_b32 s0, s10, 3
	v_readlane_b32 s1, v254, 22
	s_add_i32 s25, s0, s1
	s_addk_i32 s25, 0xfc00
	v_mov_b32_e32 v2, v0
	s_cmpk_gt_i32 s25, 0x93f
	s_cbranch_scc1 .LBB0_453
	s_add_i32 s33, s25, 0x3c0
	s_mov_b32 s26, 0
	s_cmpk_lt_i32 s25, 0xfec0
	s_movk_i32 s11, 0x400
	s_cbranch_scc1 .LBB0_413
	s_cmpk_gt_u32 s33, 0x2bf
	s_cbranch_scc0 .LBB0_414
	s_cmp_lt_u32 s25, 0xfffffc40
	s_cbranch_scc0 .LBB0_415
	s_cmpk_lt_u32 s33, 0x940
	s_cbranch_scc1 .LBB0_416
	s_cmpk_gt_u32 s33, 0xbff
	s_cbranch_scc0 .LBB0_417
	v_readlane_b32 s52, v254, 2
	v_readlane_b32 s62, v254, 12
	v_readlane_b32 s63, v254, 13
	v_readlane_b32 s64, v254, 14
	v_readlane_b32 s65, v254, 15
	s_add_i32 s24, s25, 0xfffff7c0
	s_mov_b64 s[0:1], 0
	v_readlane_b32 s53, v254, 3
	v_readlane_b32 s54, v254, 4
	v_readlane_b32 s55, v254, 5
	v_readlane_b32 s56, v254, 6
	v_readlane_b32 s57, v254, 7
	v_readlane_b32 s58, v254, 8
	v_readlane_b32 s59, v254, 9
	v_readlane_b32 s60, v254, 10
	v_readlane_b32 s61, v254, 11
	v_readlane_b32 s66, v254, 16
	v_readlane_b32 s67, v254, 17
	s_mov_b64 s[4:5], s[62:63]
	s_mov_b64 s[6:7], s[64:65]
	s_branch .LBB0_418
